# v91 + GDN scan loop latch: step counter and exit mask from two scalar instructions instead of VALU add + readfirstlane (loop-edge edit)
# speedup vs baseline: 1.0051x; 1.0028x over previous
; __device__ __forceinline__ void gdn_chain(LAS unsigned char* lds, const GdnP& P, const float* out_norm, int bh, const int tid) {
;     ...
;     for (int n = 0; n < 64; ++n) {
;         const int row0 = (b * 64 + n) * 64;
;         chain_load(nxt, P, b, h, n < 63 ? n + 1 : n, w, mt, nh, lane, tid);
;     ...
;         cur = nxt;
;     }
.LBB0_1125:
	s_or_b64 exec, exec, s[30:31]
	s_add_u32 s47, s47, 1
	s_cselect_b64 s[30:31], exec, 0
	s_waitcnt vmcnt(4)
	v_mov_b64_e32 v[84:85], v[88:89]
	v_add_u32_e32 v136, 64, v136
	s_andn2_b64 vcc, exec, s[30:31]
	v_mov_b64_e32 v[86:87], v[90:91]
	s_cbranch_vccz .LBB0_1120
